# stack + final LayerNorm pass rewritten: 4 rows per wave per iteration in flight, gain/bias vectors hoisted out of the row loop
# speedup vs baseline: 1.0401x; 1.0042x over previous
; __device__ __forceinline__ float lo_bf(unsigned x) { return __uint_as_float(x << 16); }
; __device__ __forceinline__ float hi_bf(unsigned x) { return __uint_as_float(x & 0xffff0000u); }
; __device__ __forceinline__ int opaque_tid() { int t = threadIdx.x; asm volatile("" : "+v"(t)); return t; }
; __device__ __forceinline__ void final_ln(float* out, const bf16_t* y, const float* st2, const float* g, const float* b) {
;     const int tid = opaque_tid(), lane = tid & 63, wv = tid >> 6;
;     for (int row = blockIdx.x * 8 + wv; row < TC; row += gridDim.x * 8) {
;         const f32x2_t pr = *(const f32x2_t*)(st2 + (size_t)row * 32 + (lane & 15) * 2);
;         float s = pr[0], q = pr[1];
; #pragma unroll
;         for (int d = 1; d < 16; d <<= 1) { s += __shfl_xor(s, d); q += __shfl_xor(q, d); }
;         const float mu = s * (1.0f / 1024.0f), rs = rsqrtf(fmaxf(q * (1.0f / 1024.0f) - mu * mu, 0.f) + LN_EPS);
; #pragma unroll
;         for (int k = 0; k < 2; ++k) { const int c8 = (k * 64 + lane) * 8; const u32x4 w = *(const u32x4*)(y + (size_t)row * 1024 + c8);
;             const f32x4 x0 = (f32x4){lo_bf(w.x), hi_bf(w.x), lo_bf(w.y), hi_bf(w.y)}, x1 = (f32x4){lo_bf(w.z), hi_bf(w.z), lo_bf(w.w), hi_bf(w.w)};
;             float* po = out + (size_t)row * 1024 + c8;
;             *(f32x4*)po = (x0 - mu) * rs * *(const f32x4*)(g + c8) + *(const f32x4*)(b + c8);
;             *(f32x4*)(po + 4) = (x1 - mu) * rs * *(const f32x4*)(g + c8 + 4) + *(const f32x4*)(b + c8 + 4); }
.LBB0_136:
	global_load_dwordx4 v[44:47], v[4:5], off
	global_load_dwordx4 v[48:51], v[4:5], off offset:16
	global_load_dwordx4 v[52:55], v[6:7], off
	global_load_dwordx4 v[56:59], v[6:7], off offset:16
	global_load_dwordx4 v[60:63], v[8:9], off
	global_load_dwordx4 v[64:67], v[8:9], off offset:16
	global_load_dwordx4 v[68:71], v[10:11], off
	global_load_dwordx4 v[72:75], v[10:11], off offset:16
	v_mov_b32_e32 v77, 0
	v_mov_b32_e32 v79, 0
	v_mov_b32_e32 v81, 0
	v_mov_b32_e32 v83, 0
.Lfln1_main:
	s_nop 0
	v_readfirstlane_b32 s98, v0
	s_nop 1
	s_mul_i32 s99, s23, 3
	s_add_i32 s99, s99, s98
	s_cmp_gt_i32 s99, 0xbfff
	s_cbranch_scc1 .Lfln1_tail
	v_mov_b32_e32 v76, v0
	v_add_u32_e32 v78, s23, v76
	v_add_u32_e32 v80, s23, v78
	v_add_u32_e32 v82, s23, v80
	v_lshlrev_b64 v[132:133], 7, v[76:77]
	v_lshl_add_u64 v[132:133], v[2:3], 0, v[132:133]
	global_load_dwordx2 v[84:85], v[132:133], off
	v_lshlrev_b64 v[132:133], 11, v[76:77]
	v_lshl_add_u64 v[132:133], v[12:13], 0, v[132:133]
	global_load_dwordx4 v[86:89], v[132:133], off
	global_load_dwordx4 v[90:93], v[132:133], off offset:1024
	v_lshlrev_b64 v[94:95], 12, v[76:77]
	v_lshl_add_u64 v[94:95], v[14:15], 0, v[94:95]
	v_lshlrev_b64 v[132:133], 7, v[78:79]
	v_lshl_add_u64 v[132:133], v[2:3], 0, v[132:133]
	global_load_dwordx2 v[96:97], v[132:133], off
	v_lshlrev_b64 v[132:133], 11, v[78:79]
	v_lshl_add_u64 v[132:133], v[12:13], 0, v[132:133]
	global_load_dwordx4 v[98:101], v[132:133], off
	global_load_dwordx4 v[102:105], v[132:133], off offset:1024
	v_lshlrev_b64 v[106:107], 12, v[78:79]
	v_lshl_add_u64 v[106:107], v[14:15], 0, v[106:107]
	v_lshlrev_b64 v[132:133], 7, v[80:81]
	v_lshl_add_u64 v[132:133], v[2:3], 0, v[132:133]
	global_load_dwordx2 v[108:109], v[132:133], off
	v_lshlrev_b64 v[132:133], 11, v[80:81]
	v_lshl_add_u64 v[132:133], v[12:13], 0, v[132:133]
	global_load_dwordx4 v[110:113], v[132:133], off
	global_load_dwordx4 v[114:117], v[132:133], off offset:1024
	v_lshlrev_b64 v[118:119], 12, v[80:81]
	v_lshl_add_u64 v[118:119], v[14:15], 0, v[118:119]
	v_lshlrev_b64 v[132:133], 7, v[82:83]
	v_lshl_add_u64 v[132:133], v[2:3], 0, v[132:133]
	global_load_dwordx2 v[120:121], v[132:133], off
	v_lshlrev_b64 v[132:133], 11, v[82:83]
	v_lshl_add_u64 v[132:133], v[12:13], 0, v[132:133]
	global_load_dwordx4 v[122:125], v[132:133], off
	global_load_dwordx4 v[126:129], v[132:133], off offset:1024
	v_lshlrev_b64 v[130:131], 12, v[82:83]
	v_lshl_add_u64 v[130:131], v[14:15], 0, v[130:131]
	v_add_u32_e32 v0, s23, v82
	s_waitcnt vmcnt(11)
	ds_bpermute_b32 v132, v16, v84
	ds_bpermute_b32 v133, v16, v85
	s_waitcnt lgkmcnt(0)
	v_pk_add_f32 v[84:85], v[84:85], v[132:133]
	ds_bpermute_b32 v132, v17, v84
	ds_bpermute_b32 v133, v17, v85
	s_waitcnt lgkmcnt(0)
	v_pk_add_f32 v[84:85], v[84:85], v[132:133]
	ds_bpermute_b32 v132, v18, v84
	ds_bpermute_b32 v133, v18, v85
	s_waitcnt lgkmcnt(0)
	v_pk_add_f32 v[84:85], v[84:85], v[132:133]
	ds_bpermute_b32 v132, v19, v84
	ds_bpermute_b32 v133, v19, v85
	s_waitcnt lgkmcnt(0)
	v_pk_add_f32 v[84:85], v[84:85], v[132:133]
	s_nop 0
	v_pk_mul_f32 v[136:137], v[84:85], s[74:75] op_sel_hi:[1,0]
	s_nop 0
	v_fma_f32 v138, -v136, v136, v137
	v_max_f32_e32 v138, 0, v138
	v_add_f32_e32 v138, 0x3727c5ac, v138
	v_mul_f32_e32 v139, 0x4b800000, v138
	v_cmp_gt_f32_e32 vcc, s75, v138
	s_nop 1
	v_cndmask_b32_e32 v138, v138, v139, vcc
	v_rsq_f32_e32 v139, v138
	s_nop 0
	v_mul_f32_e32 v140, 0x45800000, v139
	v_cndmask_b32_e32 v140, v139, v140, vcc
	s_waitcnt vmcnt(10)
	v_lshlrev_b32_e32 v142, 16, v86
	v_and_b32_e32 v143, 0xffff0000, v86
	v_lshlrev_b32_e32 v144, 16, v87
	v_and_b32_e32 v145, 0xffff0000, v87
	v_sub_f32_e32 v142, v142, v136
	v_sub_f32_e32 v143, v143, v136
	v_sub_f32_e32 v144, v144, v136
	v_sub_f32_e32 v145, v145, v136
	v_pk_mul_f32 v[142:143], v[142:143], v[140:141] op_sel_hi:[1,0]
	v_pk_mul_f32 v[144:145], v[144:145], v[140:141] op_sel_hi:[1,0]
	v_pk_fma_f32 v[146:147], v[44:45], v[142:143], v[52:53]
	v_pk_fma_f32 v[148:149], v[46:47], v[144:145], v[54:55]
	global_store_dwordx4 v[94:95], v[146:149], off
	v_lshlrev_b32_e32 v142, 16, v88
	v_and_b32_e32 v143, 0xffff0000, v88
	v_lshlrev_b32_e32 v144, 16, v89
	v_and_b32_e32 v145, 0xffff0000, v89
	v_sub_f32_e32 v142, v142, v136
	v_sub_f32_e32 v143, v143, v136
	v_sub_f32_e32 v144, v144, v136
	v_sub_f32_e32 v145, v145, v136
	v_pk_mul_f32 v[142:143], v[142:143], v[140:141] op_sel_hi:[1,0]
	v_pk_mul_f32 v[144:145], v[144:145], v[140:141] op_sel_hi:[1,0]
	v_pk_fma_f32 v[150:151], v[48:49], v[142:143], v[56:57]
	v_pk_fma_f32 v[152:153], v[50:51], v[144:145], v[58:59]
	global_store_dwordx4 v[94:95], v[150:153], off offset:16
	s_waitcnt vmcnt(11)
	v_lshlrev_b32_e32 v142, 16, v90
	v_and_b32_e32 v143, 0xffff0000, v90
	v_lshlrev_b32_e32 v144, 16, v91
	v_and_b32_e32 v145, 0xffff0000, v91
	v_sub_f32_e32 v142, v142, v136
	v_sub_f32_e32 v143, v143, v136
	v_sub_f32_e32 v144, v144, v136
	v_sub_f32_e32 v145, v145, v136
	v_pk_mul_f32 v[142:143], v[142:143], v[140:141] op_sel_hi:[1,0]
	v_pk_mul_f32 v[144:145], v[144:145], v[140:141] op_sel_hi:[1,0]
	v_pk_fma_f32 v[154:155], v[60:61], v[142:143], v[68:69]
	v_pk_fma_f32 v[156:157], v[62:63], v[144:145], v[70:71]
	global_store_dwordx4 v[94:95], v[154:157], off offset:2048
	v_lshlrev_b32_e32 v142, 16, v92
	v_and_b32_e32 v143, 0xffff0000, v92
	v_lshlrev_b32_e32 v144, 16, v93
	v_and_b32_e32 v145, 0xffff0000, v93
	v_sub_f32_e32 v142, v142, v136
	v_sub_f32_e32 v143, v143, v136
	v_sub_f32_e32 v144, v144, v136
	v_sub_f32_e32 v145, v145, v136
	v_pk_mul_f32 v[142:143], v[142:143], v[140:141] op_sel_hi:[1,0]
	v_pk_mul_f32 v[144:145], v[144:145], v[140:141] op_sel_hi:[1,0]
	v_pk_fma_f32 v[158:159], v[64:65], v[142:143], v[72:73]
	v_pk_fma_f32 v[160:161], v[66:67], v[144:145], v[74:75]
	global_store_dwordx4 v[94:95], v[158:161], off offset:2064
	s_waitcnt vmcnt(12)
; __device__ __forceinline__ float lo_bf(unsigned x) { return __uint_as_float(x << 16); }
; __device__ __forceinline__ float hi_bf(unsigned x) { return __uint_as_float(x & 0xffff0000u); }
; __device__ __forceinline__ int opaque_tid() { int t = threadIdx.x; asm volatile("" : "+v"(t)); return t; }
; __device__ __forceinline__ void final_ln(float* out, const bf16_t* y, const float* st2, const float* g, const float* b) {
;     const int tid = opaque_tid(), lane = tid & 63, wv = tid >> 6;
;     for (int row = blockIdx.x * 8 + wv; row < TC; row += gridDim.x * 8) {
;         const f32x2_t pr = *(const f32x2_t*)(st2 + (size_t)row * 32 + (lane & 15) * 2);
;         float s = pr[0], q = pr[1];
; #pragma unroll
;         for (int d = 1; d < 16; d <<= 1) { s += __shfl_xor(s, d); q += __shfl_xor(q, d); }
;         const float mu = s * (1.0f / 1024.0f), rs = rsqrtf(fmaxf(q * (1.0f / 1024.0f) - mu * mu, 0.f) + LN_EPS);
; #pragma unroll
;         for (int k = 0; k < 2; ++k) { const int c8 = (k * 64 + lane) * 8; const u32x4 w = *(const u32x4*)(y + (size_t)row * 1024 + c8);
;             const f32x4 x0 = (f32x4){lo_bf(w.x), hi_bf(w.x), lo_bf(w.y), hi_bf(w.y)}, x1 = (f32x4){lo_bf(w.z), hi_bf(w.z), lo_bf(w.w), hi_bf(w.w)};
;             float* po = out + (size_t)row * 1024 + c8;
;             *(f32x4*)po = (x0 - mu) * rs * *(const f32x4*)(g + c8) + *(const f32x4*)(b + c8);
;             *(f32x4*)(po + 4) = (x1 - mu) * rs * *(const f32x4*)(g + c8 + 4) + *(const f32x4*)(b + c8 + 4); }
	ds_bpermute_b32 v132, v16, v96
	ds_bpermute_b32 v133, v16, v97
	s_waitcnt lgkmcnt(0)
	v_pk_add_f32 v[96:97], v[96:97], v[132:133]
	ds_bpermute_b32 v132, v17, v96
	ds_bpermute_b32 v133, v17, v97
	s_waitcnt lgkmcnt(0)
	v_pk_add_f32 v[96:97], v[96:97], v[132:133]
	ds_bpermute_b32 v132, v18, v96
	ds_bpermute_b32 v133, v18, v97
	s_waitcnt lgkmcnt(0)
	v_pk_add_f32 v[96:97], v[96:97], v[132:133]
	ds_bpermute_b32 v132, v19, v96
	ds_bpermute_b32 v133, v19, v97
	s_waitcnt lgkmcnt(0)
	v_pk_add_f32 v[96:97], v[96:97], v[132:133]
	s_nop 0
	v_pk_mul_f32 v[136:137], v[96:97], s[74:75] op_sel_hi:[1,0]
	s_nop 0
	v_fma_f32 v138, -v136, v136, v137
	v_max_f32_e32 v138, 0, v138
	v_add_f32_e32 v138, 0x3727c5ac, v138
	v_mul_f32_e32 v139, 0x4b800000, v138
	v_cmp_gt_f32_e32 vcc, s75, v138
	s_nop 1
	v_cndmask_b32_e32 v138, v138, v139, vcc
	v_rsq_f32_e32 v139, v138
	s_nop 0
	v_mul_f32_e32 v140, 0x45800000, v139
	v_cndmask_b32_e32 v140, v139, v140, vcc
	s_waitcnt vmcnt(11)
	v_lshlrev_b32_e32 v142, 16, v98
	v_and_b32_e32 v143, 0xffff0000, v98
	v_lshlrev_b32_e32 v144, 16, v99
	v_and_b32_e32 v145, 0xffff0000, v99
	v_sub_f32_e32 v142, v142, v136
	v_sub_f32_e32 v143, v143, v136
	v_sub_f32_e32 v144, v144, v136
	v_sub_f32_e32 v145, v145, v136
	v_pk_mul_f32 v[142:143], v[142:143], v[140:141] op_sel_hi:[1,0]
	v_pk_mul_f32 v[144:145], v[144:145], v[140:141] op_sel_hi:[1,0]
	v_pk_fma_f32 v[146:147], v[44:45], v[142:143], v[52:53]
	v_pk_fma_f32 v[148:149], v[46:47], v[144:145], v[54:55]
	global_store_dwordx4 v[106:107], v[146:149], off
	v_lshlrev_b32_e32 v142, 16, v100
	v_and_b32_e32 v143, 0xffff0000, v100
	v_lshlrev_b32_e32 v144, 16, v101
	v_and_b32_e32 v145, 0xffff0000, v101
	v_sub_f32_e32 v142, v142, v136
	v_sub_f32_e32 v143, v143, v136
	v_sub_f32_e32 v144, v144, v136
	v_sub_f32_e32 v145, v145, v136
	v_pk_mul_f32 v[142:143], v[142:143], v[140:141] op_sel_hi:[1,0]
	v_pk_mul_f32 v[144:145], v[144:145], v[140:141] op_sel_hi:[1,0]
	v_pk_fma_f32 v[150:151], v[48:49], v[142:143], v[56:57]
	v_pk_fma_f32 v[152:153], v[50:51], v[144:145], v[58:59]
	global_store_dwordx4 v[106:107], v[150:153], off offset:16
	s_waitcnt vmcnt(12)
	v_lshlrev_b32_e32 v142, 16, v102
	v_and_b32_e32 v143, 0xffff0000, v102
	v_lshlrev_b32_e32 v144, 16, v103
	v_and_b32_e32 v145, 0xffff0000, v103
	v_sub_f32_e32 v142, v142, v136
	v_sub_f32_e32 v143, v143, v136
	v_sub_f32_e32 v144, v144, v136
	v_sub_f32_e32 v145, v145, v136
	v_pk_mul_f32 v[142:143], v[142:143], v[140:141] op_sel_hi:[1,0]
	v_pk_mul_f32 v[144:145], v[144:145], v[140:141] op_sel_hi:[1,0]
	v_pk_fma_f32 v[154:155], v[60:61], v[142:143], v[68:69]
	v_pk_fma_f32 v[156:157], v[62:63], v[144:145], v[70:71]
	global_store_dwordx4 v[106:107], v[154:157], off offset:2048
	v_lshlrev_b32_e32 v142, 16, v104
	v_and_b32_e32 v143, 0xffff0000, v104
	v_lshlrev_b32_e32 v144, 16, v105
	v_and_b32_e32 v145, 0xffff0000, v105
	v_sub_f32_e32 v142, v142, v136
	v_sub_f32_e32 v143, v143, v136
	v_sub_f32_e32 v144, v144, v136
	v_sub_f32_e32 v145, v145, v136
	v_pk_mul_f32 v[142:143], v[142:143], v[140:141] op_sel_hi:[1,0]
	v_pk_mul_f32 v[144:145], v[144:145], v[140:141] op_sel_hi:[1,0]
	v_pk_fma_f32 v[158:159], v[64:65], v[142:143], v[72:73]
	v_pk_fma_f32 v[160:161], v[66:67], v[144:145], v[74:75]
	global_store_dwordx4 v[106:107], v[158:161], off offset:2064
	s_waitcnt vmcnt(13)
	ds_bpermute_b32 v132, v16, v108
	ds_bpermute_b32 v133, v16, v109
	s_waitcnt lgkmcnt(0)
	v_pk_add_f32 v[108:109], v[108:109], v[132:133]
	ds_bpermute_b32 v132, v17, v108
	ds_bpermute_b32 v133, v17, v109
	s_waitcnt lgkmcnt(0)
	v_pk_add_f32 v[108:109], v[108:109], v[132:133]
	ds_bpermute_b32 v132, v18, v108
	ds_bpermute_b32 v133, v18, v109
	s_waitcnt lgkmcnt(0)
	v_pk_add_f32 v[108:109], v[108:109], v[132:133]
	ds_bpermute_b32 v132, v19, v108
	ds_bpermute_b32 v133, v19, v109
	s_waitcnt lgkmcnt(0)
	v_pk_add_f32 v[108:109], v[108:109], v[132:133]
	s_nop 0
	v_pk_mul_f32 v[136:137], v[108:109], s[74:75] op_sel_hi:[1,0]
	s_nop 0
	v_fma_f32 v138, -v136, v136, v137
	v_max_f32_e32 v138, 0, v138
	v_add_f32_e32 v138, 0x3727c5ac, v138
	v_mul_f32_e32 v139, 0x4b800000, v138
	v_cmp_gt_f32_e32 vcc, s75, v138
	s_nop 1
	v_cndmask_b32_e32 v138, v138, v139, vcc
	v_rsq_f32_e32 v139, v138
	s_nop 0
	v_mul_f32_e32 v140, 0x45800000, v139
	v_cndmask_b32_e32 v140, v139, v140, vcc
	s_waitcnt vmcnt(12)
	v_lshlrev_b32_e32 v142, 16, v110
	v_and_b32_e32 v143, 0xffff0000, v110
	v_lshlrev_b32_e32 v144, 16, v111
	v_and_b32_e32 v145, 0xffff0000, v111
	v_sub_f32_e32 v142, v142, v136
	v_sub_f32_e32 v143, v143, v136
	v_sub_f32_e32 v144, v144, v136
	v_sub_f32_e32 v145, v145, v136
	v_pk_mul_f32 v[142:143], v[142:143], v[140:141] op_sel_hi:[1,0]
	v_pk_mul_f32 v[144:145], v[144:145], v[140:141] op_sel_hi:[1,0]
	v_pk_fma_f32 v[146:147], v[44:45], v[142:143], v[52:53]
	v_pk_fma_f32 v[148:149], v[46:47], v[144:145], v[54:55]
	global_store_dwordx4 v[118:119], v[146:149], off
	v_lshlrev_b32_e32 v142, 16, v112
	v_and_b32_e32 v143, 0xffff0000, v112
	v_lshlrev_b32_e32 v144, 16, v113
	v_and_b32_e32 v145, 0xffff0000, v113
	v_sub_f32_e32 v142, v142, v136
	v_sub_f32_e32 v143, v143, v136
	v_sub_f32_e32 v144, v144, v136
	v_sub_f32_e32 v145, v145, v136
	v_pk_mul_f32 v[142:143], v[142:143], v[140:141] op_sel_hi:[1,0]
	v_pk_mul_f32 v[144:145], v[144:145], v[140:141] op_sel_hi:[1,0]
	v_pk_fma_f32 v[150:151], v[48:49], v[142:143], v[56:57]
	v_pk_fma_f32 v[152:153], v[50:51], v[144:145], v[58:59]
	global_store_dwordx4 v[118:119], v[150:153], off offset:16
	s_waitcnt vmcnt(13)
; __device__ __forceinline__ float lo_bf(unsigned x) { return __uint_as_float(x << 16); }
; __device__ __forceinline__ float hi_bf(unsigned x) { return __uint_as_float(x & 0xffff0000u); }
; __device__ __forceinline__ int opaque_tid() { int t = threadIdx.x; asm volatile("" : "+v"(t)); return t; }
; __device__ __forceinline__ void final_ln(float* out, const bf16_t* y, const float* st2, const float* g, const float* b) {
;     const int tid = opaque_tid(), lane = tid & 63, wv = tid >> 6;
;     for (int row = blockIdx.x * 8 + wv; row < TC; row += gridDim.x * 8) {
;         const f32x2_t pr = *(const f32x2_t*)(st2 + (size_t)row * 32 + (lane & 15) * 2);
;         float s = pr[0], q = pr[1];
; #pragma unroll
;         for (int d = 1; d < 16; d <<= 1) { s += __shfl_xor(s, d); q += __shfl_xor(q, d); }
;         const float mu = s * (1.0f / 1024.0f), rs = rsqrtf(fmaxf(q * (1.0f / 1024.0f) - mu * mu, 0.f) + LN_EPS);
; #pragma unroll
;         for (int k = 0; k < 2; ++k) { const int c8 = (k * 64 + lane) * 8; const u32x4 w = *(const u32x4*)(y + (size_t)row * 1024 + c8);
;             const f32x4 x0 = (f32x4){lo_bf(w.x), hi_bf(w.x), lo_bf(w.y), hi_bf(w.y)}, x1 = (f32x4){lo_bf(w.z), hi_bf(w.z), lo_bf(w.w), hi_bf(w.w)};
;             float* po = out + (size_t)row * 1024 + c8;
;             *(f32x4*)po = (x0 - mu) * rs * *(const f32x4*)(g + c8) + *(const f32x4*)(b + c8);
;             *(f32x4*)(po + 4) = (x1 - mu) * rs * *(const f32x4*)(g + c8 + 4) + *(const f32x4*)(b + c8 + 4); }
	v_lshlrev_b32_e32 v142, 16, v114
	v_and_b32_e32 v143, 0xffff0000, v114
	v_lshlrev_b32_e32 v144, 16, v115
	v_and_b32_e32 v145, 0xffff0000, v115
	v_sub_f32_e32 v142, v142, v136
	v_sub_f32_e32 v143, v143, v136
	v_sub_f32_e32 v144, v144, v136
	v_sub_f32_e32 v145, v145, v136
	v_pk_mul_f32 v[142:143], v[142:143], v[140:141] op_sel_hi:[1,0]
	v_pk_mul_f32 v[144:145], v[144:145], v[140:141] op_sel_hi:[1,0]
	v_pk_fma_f32 v[154:155], v[60:61], v[142:143], v[68:69]
	v_pk_fma_f32 v[156:157], v[62:63], v[144:145], v[70:71]
	global_store_dwordx4 v[118:119], v[154:157], off offset:2048
	v_lshlrev_b32_e32 v142, 16, v116
	v_and_b32_e32 v143, 0xffff0000, v116
	v_lshlrev_b32_e32 v144, 16, v117
	v_and_b32_e32 v145, 0xffff0000, v117
	v_sub_f32_e32 v142, v142, v136
	v_sub_f32_e32 v143, v143, v136
	v_sub_f32_e32 v144, v144, v136
	v_sub_f32_e32 v145, v145, v136
	v_pk_mul_f32 v[142:143], v[142:143], v[140:141] op_sel_hi:[1,0]
	v_pk_mul_f32 v[144:145], v[144:145], v[140:141] op_sel_hi:[1,0]
	v_pk_fma_f32 v[158:159], v[64:65], v[142:143], v[72:73]
	v_pk_fma_f32 v[160:161], v[66:67], v[144:145], v[74:75]
	global_store_dwordx4 v[118:119], v[158:161], off offset:2064
	s_waitcnt vmcnt(14)
	ds_bpermute_b32 v132, v16, v120
	ds_bpermute_b32 v133, v16, v121
	s_waitcnt lgkmcnt(0)
	v_pk_add_f32 v[120:121], v[120:121], v[132:133]
	ds_bpermute_b32 v132, v17, v120
	ds_bpermute_b32 v133, v17, v121
	s_waitcnt lgkmcnt(0)
	v_pk_add_f32 v[120:121], v[120:121], v[132:133]
	ds_bpermute_b32 v132, v18, v120
	ds_bpermute_b32 v133, v18, v121
	s_waitcnt lgkmcnt(0)
	v_pk_add_f32 v[120:121], v[120:121], v[132:133]
	ds_bpermute_b32 v132, v19, v120
	ds_bpermute_b32 v133, v19, v121
	s_waitcnt lgkmcnt(0)
	v_pk_add_f32 v[120:121], v[120:121], v[132:133]
	s_nop 0
	v_pk_mul_f32 v[136:137], v[120:121], s[74:75] op_sel_hi:[1,0]
	s_nop 0
	v_fma_f32 v138, -v136, v136, v137
	v_max_f32_e32 v138, 0, v138
	v_add_f32_e32 v138, 0x3727c5ac, v138
	v_mul_f32_e32 v139, 0x4b800000, v138
	v_cmp_gt_f32_e32 vcc, s75, v138
	s_nop 1
	v_cndmask_b32_e32 v138, v138, v139, vcc
	v_rsq_f32_e32 v139, v138
	s_nop 0
	v_mul_f32_e32 v140, 0x45800000, v139
	v_cndmask_b32_e32 v140, v139, v140, vcc
	s_waitcnt vmcnt(13)
	v_lshlrev_b32_e32 v142, 16, v122
	v_and_b32_e32 v143, 0xffff0000, v122
	v_lshlrev_b32_e32 v144, 16, v123
	v_and_b32_e32 v145, 0xffff0000, v123
	v_sub_f32_e32 v142, v142, v136
	v_sub_f32_e32 v143, v143, v136
	v_sub_f32_e32 v144, v144, v136
	v_sub_f32_e32 v145, v145, v136
	v_pk_mul_f32 v[142:143], v[142:143], v[140:141] op_sel_hi:[1,0]
	v_pk_mul_f32 v[144:145], v[144:145], v[140:141] op_sel_hi:[1,0]
	v_pk_fma_f32 v[146:147], v[44:45], v[142:143], v[52:53]
	v_pk_fma_f32 v[148:149], v[46:47], v[144:145], v[54:55]
	global_store_dwordx4 v[130:131], v[146:149], off
	v_lshlrev_b32_e32 v142, 16, v124
	v_and_b32_e32 v143, 0xffff0000, v124
	v_lshlrev_b32_e32 v144, 16, v125
	v_and_b32_e32 v145, 0xffff0000, v125
	v_sub_f32_e32 v142, v142, v136
	v_sub_f32_e32 v143, v143, v136
	v_sub_f32_e32 v144, v144, v136
	v_sub_f32_e32 v145, v145, v136
	v_pk_mul_f32 v[142:143], v[142:143], v[140:141] op_sel_hi:[1,0]
	v_pk_mul_f32 v[144:145], v[144:145], v[140:141] op_sel_hi:[1,0]
	v_pk_fma_f32 v[150:151], v[48:49], v[142:143], v[56:57]
	v_pk_fma_f32 v[152:153], v[50:51], v[144:145], v[58:59]
	global_store_dwordx4 v[130:131], v[150:153], off offset:16
	s_waitcnt vmcnt(14)
	v_lshlrev_b32_e32 v142, 16, v126
	v_and_b32_e32 v143, 0xffff0000, v126
	v_lshlrev_b32_e32 v144, 16, v127
	v_and_b32_e32 v145, 0xffff0000, v127
	v_sub_f32_e32 v142, v142, v136
	v_sub_f32_e32 v143, v143, v136
	v_sub_f32_e32 v144, v144, v136
	v_sub_f32_e32 v145, v145, v136
	v_pk_mul_f32 v[142:143], v[142:143], v[140:141] op_sel_hi:[1,0]
	v_pk_mul_f32 v[144:145], v[144:145], v[140:141] op_sel_hi:[1,0]
	v_pk_fma_f32 v[154:155], v[60:61], v[142:143], v[68:69]
	v_pk_fma_f32 v[156:157], v[62:63], v[144:145], v[70:71]
	global_store_dwordx4 v[130:131], v[154:157], off offset:2048
	v_lshlrev_b32_e32 v142, 16, v128
	v_and_b32_e32 v143, 0xffff0000, v128
	v_lshlrev_b32_e32 v144, 16, v129
	v_and_b32_e32 v145, 0xffff0000, v129
	v_sub_f32_e32 v142, v142, v136
	v_sub_f32_e32 v143, v143, v136
	v_sub_f32_e32 v144, v144, v136
	v_sub_f32_e32 v145, v145, v136
	v_pk_mul_f32 v[142:143], v[142:143], v[140:141] op_sel_hi:[1,0]
	v_pk_mul_f32 v[144:145], v[144:145], v[140:141] op_sel_hi:[1,0]
	v_pk_fma_f32 v[158:159], v[64:65], v[142:143], v[72:73]
	v_pk_fma_f32 v[160:161], v[66:67], v[144:145], v[74:75]
	global_store_dwordx4 v[130:131], v[158:161], off offset:2064
	s_branch .Lfln1_main
.Lfln1_tail:
	s_cmp_gt_i32 s98, 0xbfff
	s_cbranch_scc1 .LBB0_137

; __device__ __forceinline__ float lo_bf(unsigned x) { return __uint_as_float(x << 16); }
; __device__ __forceinline__ float hi_bf(unsigned x) { return __uint_as_float(x & 0xffff0000u); }
; __device__ __forceinline__ int opaque_tid() { int t = threadIdx.x; asm volatile("" : "+v"(t)); return t; }
; __device__ __forceinline__ void final_ln(float* out, const bf16_t* y, const float* st2, const float* g, const float* b) {
;     const int tid = opaque_tid(), lane = tid & 63, wv = tid >> 6;
;     for (int row = blockIdx.x * 8 + wv; row < TC; row += gridDim.x * 8) {
;         const f32x2_t pr = *(const f32x2_t*)(st2 + (size_t)row * 32 + (lane & 15) * 2);
;         float s = pr[0], q = pr[1];
; #pragma unroll
;         for (int d = 1; d < 16; d <<= 1) { s += __shfl_xor(s, d); q += __shfl_xor(q, d); }
;         const float mu = s * (1.0f / 1024.0f), rs = rsqrtf(fmaxf(q * (1.0f / 1024.0f) - mu * mu, 0.f) + LN_EPS);
; #pragma unroll
;         for (int k = 0; k < 2; ++k) { const int c8 = (k * 64 + lane) * 8; const u32x4 w = *(const u32x4*)(y + (size_t)row * 1024 + c8);
;             const f32x4 x0 = (f32x4){lo_bf(w.x), hi_bf(w.x), lo_bf(w.y), hi_bf(w.y)}, x1 = (f32x4){lo_bf(w.z), hi_bf(w.z), lo_bf(w.w), hi_bf(w.w)};
;             float* po = out + (size_t)row * 1024 + c8;
;             *(f32x4*)po = (x0 - mu) * rs * *(const f32x4*)(g + c8) + *(const f32x4*)(b + c8);
;             *(f32x4*)(po + 4) = (x1 - mu) * rs * *(const f32x4*)(g + c8 + 4) + *(const f32x4*)(b + c8 + 4); }
.Lfln2_main:
	s_nop 0
	v_readfirstlane_b32 s98, v0
	s_nop 1
	s_mul_i32 s99, s23, 3
	s_add_i32 s99, s99, s98
	s_cmp_gt_i32 s99, 0xbfff
	s_cbranch_scc1 .Lfln2_tail
	v_mov_b32_e32 v76, v0
	v_add_u32_e32 v78, s23, v76
	v_add_u32_e32 v80, s23, v78
	v_add_u32_e32 v82, s23, v80
	v_lshlrev_b64 v[132:133], 7, v[76:77]
	v_lshl_add_u64 v[132:133], v[2:3], 0, v[132:133]
	global_load_dwordx2 v[84:85], v[132:133], off
	v_lshlrev_b64 v[132:133], 11, v[76:77]
	v_lshl_add_u64 v[132:133], v[12:13], 0, v[132:133]
	global_load_dwordx4 v[86:89], v[132:133], off
	global_load_dwordx4 v[90:93], v[132:133], off offset:1024
	v_lshlrev_b64 v[94:95], 12, v[76:77]
	v_lshl_add_u64 v[94:95], v[14:15], 0, v[94:95]
	v_lshlrev_b64 v[132:133], 7, v[78:79]
	v_lshl_add_u64 v[132:133], v[2:3], 0, v[132:133]
	global_load_dwordx2 v[96:97], v[132:133], off
	v_lshlrev_b64 v[132:133], 11, v[78:79]
	v_lshl_add_u64 v[132:133], v[12:13], 0, v[132:133]
	global_load_dwordx4 v[98:101], v[132:133], off
	global_load_dwordx4 v[102:105], v[132:133], off offset:1024
	v_lshlrev_b64 v[106:107], 12, v[78:79]
	v_lshl_add_u64 v[106:107], v[14:15], 0, v[106:107]
	v_lshlrev_b64 v[132:133], 7, v[80:81]
	v_lshl_add_u64 v[132:133], v[2:3], 0, v[132:133]
	global_load_dwordx2 v[108:109], v[132:133], off
	v_lshlrev_b64 v[132:133], 11, v[80:81]
	v_lshl_add_u64 v[132:133], v[12:13], 0, v[132:133]
	global_load_dwordx4 v[110:113], v[132:133], off
	global_load_dwordx4 v[114:117], v[132:133], off offset:1024
	v_lshlrev_b64 v[118:119], 12, v[80:81]
	v_lshl_add_u64 v[118:119], v[14:15], 0, v[118:119]
	v_lshlrev_b64 v[132:133], 7, v[82:83]
	v_lshl_add_u64 v[132:133], v[2:3], 0, v[132:133]
	global_load_dwordx2 v[120:121], v[132:133], off
	v_lshlrev_b64 v[132:133], 11, v[82:83]
	v_lshl_add_u64 v[132:133], v[12:13], 0, v[132:133]
	global_load_dwordx4 v[122:125], v[132:133], off
	global_load_dwordx4 v[126:129], v[132:133], off offset:1024
	v_lshlrev_b64 v[130:131], 12, v[82:83]
	v_lshl_add_u64 v[130:131], v[14:15], 0, v[130:131]
	v_add_u32_e32 v0, s23, v82
	s_waitcnt vmcnt(11)
	ds_bpermute_b32 v132, v16, v84
	ds_bpermute_b32 v133, v16, v85
	s_waitcnt lgkmcnt(0)
	v_pk_add_f32 v[84:85], v[84:85], v[132:133]
	ds_bpermute_b32 v132, v17, v84
	ds_bpermute_b32 v133, v17, v85
	s_waitcnt lgkmcnt(0)
	v_pk_add_f32 v[84:85], v[84:85], v[132:133]
	ds_bpermute_b32 v132, v18, v84
	ds_bpermute_b32 v133, v18, v85
	s_waitcnt lgkmcnt(0)
	v_pk_add_f32 v[84:85], v[84:85], v[132:133]
	ds_bpermute_b32 v132, v19, v84
	ds_bpermute_b32 v133, v19, v85
	s_waitcnt lgkmcnt(0)
	v_pk_add_f32 v[84:85], v[84:85], v[132:133]
	s_nop 0
	v_pk_mul_f32 v[136:137], v[84:85], s[2:3] op_sel_hi:[1,0]
	s_nop 0
	v_fma_f32 v138, -v136, v136, v137
	v_max_f32_e32 v138, 0, v138
	v_add_f32_e32 v138, 0x3727c5ac, v138
	v_mul_f32_e32 v139, 0x4b800000, v138
	v_cmp_gt_f32_e32 vcc, s3, v138
	s_nop 1
	v_cndmask_b32_e32 v138, v138, v139, vcc
	v_rsq_f32_e32 v139, v138
	s_nop 0
	v_mul_f32_e32 v140, 0x45800000, v139
	v_cndmask_b32_e32 v140, v139, v140, vcc
	s_waitcnt vmcnt(10)
	v_lshlrev_b32_e32 v142, 16, v86
	v_and_b32_e32 v143, 0xffff0000, v86
	v_lshlrev_b32_e32 v144, 16, v87
	v_and_b32_e32 v145, 0xffff0000, v87
	v_sub_f32_e32 v142, v142, v136
	v_sub_f32_e32 v143, v143, v136
	v_sub_f32_e32 v144, v144, v136
	v_sub_f32_e32 v145, v145, v136
	v_pk_mul_f32 v[142:143], v[142:143], v[140:141] op_sel_hi:[1,0]
	v_pk_mul_f32 v[144:145], v[144:145], v[140:141] op_sel_hi:[1,0]
	v_pk_fma_f32 v[146:147], v[44:45], v[142:143], v[52:53]
	v_pk_fma_f32 v[148:149], v[46:47], v[144:145], v[54:55]
	global_store_dwordx4 v[94:95], v[146:149], off
	v_lshlrev_b32_e32 v142, 16, v88
	v_and_b32_e32 v143, 0xffff0000, v88
	v_lshlrev_b32_e32 v144, 16, v89
	v_and_b32_e32 v145, 0xffff0000, v89
	v_sub_f32_e32 v142, v142, v136
	v_sub_f32_e32 v143, v143, v136
	v_sub_f32_e32 v144, v144, v136
	v_sub_f32_e32 v145, v145, v136
	v_pk_mul_f32 v[142:143], v[142:143], v[140:141] op_sel_hi:[1,0]
	v_pk_mul_f32 v[144:145], v[144:145], v[140:141] op_sel_hi:[1,0]
	v_pk_fma_f32 v[150:151], v[48:49], v[142:143], v[56:57]
	v_pk_fma_f32 v[152:153], v[50:51], v[144:145], v[58:59]
	global_store_dwordx4 v[94:95], v[150:153], off offset:16
	s_waitcnt vmcnt(11)
	v_lshlrev_b32_e32 v142, 16, v90
	v_and_b32_e32 v143, 0xffff0000, v90
	v_lshlrev_b32_e32 v144, 16, v91
	v_and_b32_e32 v145, 0xffff0000, v91
	v_sub_f32_e32 v142, v142, v136
	v_sub_f32_e32 v143, v143, v136
	v_sub_f32_e32 v144, v144, v136
	v_sub_f32_e32 v145, v145, v136
	v_pk_mul_f32 v[142:143], v[142:143], v[140:141] op_sel_hi:[1,0]
	v_pk_mul_f32 v[144:145], v[144:145], v[140:141] op_sel_hi:[1,0]
	v_pk_fma_f32 v[154:155], v[60:61], v[142:143], v[68:69]
	v_pk_fma_f32 v[156:157], v[62:63], v[144:145], v[70:71]
	global_store_dwordx4 v[94:95], v[154:157], off offset:2048
	v_lshlrev_b32_e32 v142, 16, v92
	v_and_b32_e32 v143, 0xffff0000, v92
	v_lshlrev_b32_e32 v144, 16, v93
	v_and_b32_e32 v145, 0xffff0000, v93
	v_sub_f32_e32 v142, v142, v136
	v_sub_f32_e32 v143, v143, v136
	v_sub_f32_e32 v144, v144, v136
	v_sub_f32_e32 v145, v145, v136
	v_pk_mul_f32 v[142:143], v[142:143], v[140:141] op_sel_hi:[1,0]
	v_pk_mul_f32 v[144:145], v[144:145], v[140:141] op_sel_hi:[1,0]
	v_pk_fma_f32 v[158:159], v[64:65], v[142:143], v[72:73]
	v_pk_fma_f32 v[160:161], v[66:67], v[144:145], v[74:75]
	global_store_dwordx4 v[94:95], v[158:161], off offset:2064
	s_waitcnt vmcnt(12)
	ds_bpermute_b32 v132, v16, v96
	ds_bpermute_b32 v133, v16, v97
	s_waitcnt lgkmcnt(0)
	v_pk_add_f32 v[96:97], v[96:97], v[132:133]
	ds_bpermute_b32 v132, v17, v96
	ds_bpermute_b32 v133, v17, v97
	s_waitcnt lgkmcnt(0)
	v_pk_add_f32 v[96:97], v[96:97], v[132:133]
	ds_bpermute_b32 v132, v18, v96
	ds_bpermute_b32 v133, v18, v97
	s_waitcnt lgkmcnt(0)
; __device__ __forceinline__ float lo_bf(unsigned x) { return __uint_as_float(x << 16); }
; __device__ __forceinline__ float hi_bf(unsigned x) { return __uint_as_float(x & 0xffff0000u); }
; __device__ __forceinline__ int opaque_tid() { int t = threadIdx.x; asm volatile("" : "+v"(t)); return t; }
; __device__ __forceinline__ void final_ln(float* out, const bf16_t* y, const float* st2, const float* g, const float* b) {
;     const int tid = opaque_tid(), lane = tid & 63, wv = tid >> 6;
;     for (int row = blockIdx.x * 8 + wv; row < TC; row += gridDim.x * 8) {
;         const f32x2_t pr = *(const f32x2_t*)(st2 + (size_t)row * 32 + (lane & 15) * 2);
;         float s = pr[0], q = pr[1];
; #pragma unroll
;         for (int d = 1; d < 16; d <<= 1) { s += __shfl_xor(s, d); q += __shfl_xor(q, d); }
;         const float mu = s * (1.0f / 1024.0f), rs = rsqrtf(fmaxf(q * (1.0f / 1024.0f) - mu * mu, 0.f) + LN_EPS);
; #pragma unroll
;         for (int k = 0; k < 2; ++k) { const int c8 = (k * 64 + lane) * 8; const u32x4 w = *(const u32x4*)(y + (size_t)row * 1024 + c8);
;             const f32x4 x0 = (f32x4){lo_bf(w.x), hi_bf(w.x), lo_bf(w.y), hi_bf(w.y)}, x1 = (f32x4){lo_bf(w.z), hi_bf(w.z), lo_bf(w.w), hi_bf(w.w)};
;             float* po = out + (size_t)row * 1024 + c8;
;             *(f32x4*)po = (x0 - mu) * rs * *(const f32x4*)(g + c8) + *(const f32x4*)(b + c8);
;             *(f32x4*)(po + 4) = (x1 - mu) * rs * *(const f32x4*)(g + c8 + 4) + *(const f32x4*)(b + c8 + 4); }
	v_pk_add_f32 v[96:97], v[96:97], v[132:133]
	ds_bpermute_b32 v132, v19, v96
	ds_bpermute_b32 v133, v19, v97
	s_waitcnt lgkmcnt(0)
	v_pk_add_f32 v[96:97], v[96:97], v[132:133]
	s_nop 0
	v_pk_mul_f32 v[136:137], v[96:97], s[2:3] op_sel_hi:[1,0]
	s_nop 0
	v_fma_f32 v138, -v136, v136, v137
	v_max_f32_e32 v138, 0, v138
	v_add_f32_e32 v138, 0x3727c5ac, v138
	v_mul_f32_e32 v139, 0x4b800000, v138
	v_cmp_gt_f32_e32 vcc, s3, v138
	s_nop 1
	v_cndmask_b32_e32 v138, v138, v139, vcc
	v_rsq_f32_e32 v139, v138
	s_nop 0
	v_mul_f32_e32 v140, 0x45800000, v139
	v_cndmask_b32_e32 v140, v139, v140, vcc
	s_waitcnt vmcnt(11)
	v_lshlrev_b32_e32 v142, 16, v98
	v_and_b32_e32 v143, 0xffff0000, v98
	v_lshlrev_b32_e32 v144, 16, v99
	v_and_b32_e32 v145, 0xffff0000, v99
	v_sub_f32_e32 v142, v142, v136
	v_sub_f32_e32 v143, v143, v136
	v_sub_f32_e32 v144, v144, v136
	v_sub_f32_e32 v145, v145, v136
	v_pk_mul_f32 v[142:143], v[142:143], v[140:141] op_sel_hi:[1,0]
	v_pk_mul_f32 v[144:145], v[144:145], v[140:141] op_sel_hi:[1,0]
	v_pk_fma_f32 v[146:147], v[44:45], v[142:143], v[52:53]
	v_pk_fma_f32 v[148:149], v[46:47], v[144:145], v[54:55]
	global_store_dwordx4 v[106:107], v[146:149], off
	v_lshlrev_b32_e32 v142, 16, v100
	v_and_b32_e32 v143, 0xffff0000, v100
	v_lshlrev_b32_e32 v144, 16, v101
	v_and_b32_e32 v145, 0xffff0000, v101
	v_sub_f32_e32 v142, v142, v136
	v_sub_f32_e32 v143, v143, v136
	v_sub_f32_e32 v144, v144, v136
	v_sub_f32_e32 v145, v145, v136
	v_pk_mul_f32 v[142:143], v[142:143], v[140:141] op_sel_hi:[1,0]
	v_pk_mul_f32 v[144:145], v[144:145], v[140:141] op_sel_hi:[1,0]
	v_pk_fma_f32 v[150:151], v[48:49], v[142:143], v[56:57]
	v_pk_fma_f32 v[152:153], v[50:51], v[144:145], v[58:59]
	global_store_dwordx4 v[106:107], v[150:153], off offset:16
	s_waitcnt vmcnt(12)
	v_lshlrev_b32_e32 v142, 16, v102
	v_and_b32_e32 v143, 0xffff0000, v102
	v_lshlrev_b32_e32 v144, 16, v103
	v_and_b32_e32 v145, 0xffff0000, v103
	v_sub_f32_e32 v142, v142, v136
	v_sub_f32_e32 v143, v143, v136
	v_sub_f32_e32 v144, v144, v136
	v_sub_f32_e32 v145, v145, v136
	v_pk_mul_f32 v[142:143], v[142:143], v[140:141] op_sel_hi:[1,0]
	v_pk_mul_f32 v[144:145], v[144:145], v[140:141] op_sel_hi:[1,0]
	v_pk_fma_f32 v[154:155], v[60:61], v[142:143], v[68:69]
	v_pk_fma_f32 v[156:157], v[62:63], v[144:145], v[70:71]
	global_store_dwordx4 v[106:107], v[154:157], off offset:2048
	v_lshlrev_b32_e32 v142, 16, v104
	v_and_b32_e32 v143, 0xffff0000, v104
	v_lshlrev_b32_e32 v144, 16, v105
	v_and_b32_e32 v145, 0xffff0000, v105
	v_sub_f32_e32 v142, v142, v136
	v_sub_f32_e32 v143, v143, v136
	v_sub_f32_e32 v144, v144, v136
	v_sub_f32_e32 v145, v145, v136
	v_pk_mul_f32 v[142:143], v[142:143], v[140:141] op_sel_hi:[1,0]
	v_pk_mul_f32 v[144:145], v[144:145], v[140:141] op_sel_hi:[1,0]
	v_pk_fma_f32 v[158:159], v[64:65], v[142:143], v[72:73]
	v_pk_fma_f32 v[160:161], v[66:67], v[144:145], v[74:75]
	global_store_dwordx4 v[106:107], v[158:161], off offset:2064
	s_waitcnt vmcnt(13)
	ds_bpermute_b32 v132, v16, v108
	ds_bpermute_b32 v133, v16, v109
	s_waitcnt lgkmcnt(0)
	v_pk_add_f32 v[108:109], v[108:109], v[132:133]
	ds_bpermute_b32 v132, v17, v108
	ds_bpermute_b32 v133, v17, v109
	s_waitcnt lgkmcnt(0)
	v_pk_add_f32 v[108:109], v[108:109], v[132:133]
	ds_bpermute_b32 v132, v18, v108
	ds_bpermute_b32 v133, v18, v109
	s_waitcnt lgkmcnt(0)
	v_pk_add_f32 v[108:109], v[108:109], v[132:133]
	ds_bpermute_b32 v132, v19, v108
	ds_bpermute_b32 v133, v19, v109
	s_waitcnt lgkmcnt(0)
	v_pk_add_f32 v[108:109], v[108:109], v[132:133]
	s_nop 0
	v_pk_mul_f32 v[136:137], v[108:109], s[2:3] op_sel_hi:[1,0]
	s_nop 0
	v_fma_f32 v138, -v136, v136, v137
	v_max_f32_e32 v138, 0, v138
	v_add_f32_e32 v138, 0x3727c5ac, v138
	v_mul_f32_e32 v139, 0x4b800000, v138
	v_cmp_gt_f32_e32 vcc, s3, v138
	s_nop 1
	v_cndmask_b32_e32 v138, v138, v139, vcc
	v_rsq_f32_e32 v139, v138
	s_nop 0
	v_mul_f32_e32 v140, 0x45800000, v139
	v_cndmask_b32_e32 v140, v139, v140, vcc
	s_waitcnt vmcnt(12)
	v_lshlrev_b32_e32 v142, 16, v110
	v_and_b32_e32 v143, 0xffff0000, v110
	v_lshlrev_b32_e32 v144, 16, v111
	v_and_b32_e32 v145, 0xffff0000, v111
	v_sub_f32_e32 v142, v142, v136
	v_sub_f32_e32 v143, v143, v136
	v_sub_f32_e32 v144, v144, v136
	v_sub_f32_e32 v145, v145, v136
	v_pk_mul_f32 v[142:143], v[142:143], v[140:141] op_sel_hi:[1,0]
	v_pk_mul_f32 v[144:145], v[144:145], v[140:141] op_sel_hi:[1,0]
	v_pk_fma_f32 v[146:147], v[44:45], v[142:143], v[52:53]
	v_pk_fma_f32 v[148:149], v[46:47], v[144:145], v[54:55]
	global_store_dwordx4 v[118:119], v[146:149], off
	v_lshlrev_b32_e32 v142, 16, v112
	v_and_b32_e32 v143, 0xffff0000, v112
	v_lshlrev_b32_e32 v144, 16, v113
	v_and_b32_e32 v145, 0xffff0000, v113
	v_sub_f32_e32 v142, v142, v136
	v_sub_f32_e32 v143, v143, v136
	v_sub_f32_e32 v144, v144, v136
	v_sub_f32_e32 v145, v145, v136
	v_pk_mul_f32 v[142:143], v[142:143], v[140:141] op_sel_hi:[1,0]
	v_pk_mul_f32 v[144:145], v[144:145], v[140:141] op_sel_hi:[1,0]
	v_pk_fma_f32 v[150:151], v[48:49], v[142:143], v[56:57]
	v_pk_fma_f32 v[152:153], v[50:51], v[144:145], v[58:59]
	global_store_dwordx4 v[118:119], v[150:153], off offset:16
	s_waitcnt vmcnt(13)
; __device__ __forceinline__ float lo_bf(unsigned x) { return __uint_as_float(x << 16); }
; __device__ __forceinline__ float hi_bf(unsigned x) { return __uint_as_float(x & 0xffff0000u); }
; __device__ __forceinline__ int opaque_tid() { int t = threadIdx.x; asm volatile("" : "+v"(t)); return t; }
; __device__ __forceinline__ void final_ln(float* out, const bf16_t* y, const float* st2, const float* g, const float* b) {
;     const int tid = opaque_tid(), lane = tid & 63, wv = tid >> 6;
;     for (int row = blockIdx.x * 8 + wv; row < TC; row += gridDim.x * 8) {
;         const f32x2_t pr = *(const f32x2_t*)(st2 + (size_t)row * 32 + (lane & 15) * 2);
;         float s = pr[0], q = pr[1];
; #pragma unroll
;         for (int d = 1; d < 16; d <<= 1) { s += __shfl_xor(s, d); q += __shfl_xor(q, d); }
;         const float mu = s * (1.0f / 1024.0f), rs = rsqrtf(fmaxf(q * (1.0f / 1024.0f) - mu * mu, 0.f) + LN_EPS);
; #pragma unroll
;         for (int k = 0; k < 2; ++k) { const int c8 = (k * 64 + lane) * 8; const u32x4 w = *(const u32x4*)(y + (size_t)row * 1024 + c8);
;             const f32x4 x0 = (f32x4){lo_bf(w.x), hi_bf(w.x), lo_bf(w.y), hi_bf(w.y)}, x1 = (f32x4){lo_bf(w.z), hi_bf(w.z), lo_bf(w.w), hi_bf(w.w)};
;             float* po = out + (size_t)row * 1024 + c8;
;             *(f32x4*)po = (x0 - mu) * rs * *(const f32x4*)(g + c8) + *(const f32x4*)(b + c8);
;             *(f32x4*)(po + 4) = (x1 - mu) * rs * *(const f32x4*)(g + c8 + 4) + *(const f32x4*)(b + c8 + 4); }
	v_lshlrev_b32_e32 v142, 16, v114
	v_and_b32_e32 v143, 0xffff0000, v114
	v_lshlrev_b32_e32 v144, 16, v115
	v_and_b32_e32 v145, 0xffff0000, v115
	v_sub_f32_e32 v142, v142, v136
	v_sub_f32_e32 v143, v143, v136
	v_sub_f32_e32 v144, v144, v136
	v_sub_f32_e32 v145, v145, v136
	v_pk_mul_f32 v[142:143], v[142:143], v[140:141] op_sel_hi:[1,0]
	v_pk_mul_f32 v[144:145], v[144:145], v[140:141] op_sel_hi:[1,0]
	v_pk_fma_f32 v[154:155], v[60:61], v[142:143], v[68:69]
	v_pk_fma_f32 v[156:157], v[62:63], v[144:145], v[70:71]
	global_store_dwordx4 v[118:119], v[154:157], off offset:2048
	v_lshlrev_b32_e32 v142, 16, v116
	v_and_b32_e32 v143, 0xffff0000, v116
	v_lshlrev_b32_e32 v144, 16, v117
	v_and_b32_e32 v145, 0xffff0000, v117
	v_sub_f32_e32 v142, v142, v136
	v_sub_f32_e32 v143, v143, v136
	v_sub_f32_e32 v144, v144, v136
	v_sub_f32_e32 v145, v145, v136
	v_pk_mul_f32 v[142:143], v[142:143], v[140:141] op_sel_hi:[1,0]
	v_pk_mul_f32 v[144:145], v[144:145], v[140:141] op_sel_hi:[1,0]
	v_pk_fma_f32 v[158:159], v[64:65], v[142:143], v[72:73]
	v_pk_fma_f32 v[160:161], v[66:67], v[144:145], v[74:75]
	global_store_dwordx4 v[118:119], v[158:161], off offset:2064
	s_waitcnt vmcnt(14)
	ds_bpermute_b32 v132, v16, v120
	ds_bpermute_b32 v133, v16, v121
	s_waitcnt lgkmcnt(0)
	v_pk_add_f32 v[120:121], v[120:121], v[132:133]
	ds_bpermute_b32 v132, v17, v120
	ds_bpermute_b32 v133, v17, v121
	s_waitcnt lgkmcnt(0)
	v_pk_add_f32 v[120:121], v[120:121], v[132:133]
	ds_bpermute_b32 v132, v18, v120
	ds_bpermute_b32 v133, v18, v121
	s_waitcnt lgkmcnt(0)
	v_pk_add_f32 v[120:121], v[120:121], v[132:133]
	ds_bpermute_b32 v132, v19, v120
	ds_bpermute_b32 v133, v19, v121
	s_waitcnt lgkmcnt(0)
	v_pk_add_f32 v[120:121], v[120:121], v[132:133]
	s_nop 0
	v_pk_mul_f32 v[136:137], v[120:121], s[2:3] op_sel_hi:[1,0]
	s_nop 0
	v_fma_f32 v138, -v136, v136, v137
	v_max_f32_e32 v138, 0, v138
	v_add_f32_e32 v138, 0x3727c5ac, v138
	v_mul_f32_e32 v139, 0x4b800000, v138
	v_cmp_gt_f32_e32 vcc, s3, v138
	s_nop 1
	v_cndmask_b32_e32 v138, v138, v139, vcc
	v_rsq_f32_e32 v139, v138
	s_nop 0
	v_mul_f32_e32 v140, 0x45800000, v139
	v_cndmask_b32_e32 v140, v139, v140, vcc
	s_waitcnt vmcnt(13)
	v_lshlrev_b32_e32 v142, 16, v122
	v_and_b32_e32 v143, 0xffff0000, v122
	v_lshlrev_b32_e32 v144, 16, v123
	v_and_b32_e32 v145, 0xffff0000, v123
	v_sub_f32_e32 v142, v142, v136
	v_sub_f32_e32 v143, v143, v136
	v_sub_f32_e32 v144, v144, v136
	v_sub_f32_e32 v145, v145, v136
	v_pk_mul_f32 v[142:143], v[142:143], v[140:141] op_sel_hi:[1,0]
	v_pk_mul_f32 v[144:145], v[144:145], v[140:141] op_sel_hi:[1,0]
	v_pk_fma_f32 v[146:147], v[44:45], v[142:143], v[52:53]
	v_pk_fma_f32 v[148:149], v[46:47], v[144:145], v[54:55]
	global_store_dwordx4 v[130:131], v[146:149], off
	v_lshlrev_b32_e32 v142, 16, v124
	v_and_b32_e32 v143, 0xffff0000, v124
	v_lshlrev_b32_e32 v144, 16, v125
	v_and_b32_e32 v145, 0xffff0000, v125
	v_sub_f32_e32 v142, v142, v136
	v_sub_f32_e32 v143, v143, v136
	v_sub_f32_e32 v144, v144, v136
	v_sub_f32_e32 v145, v145, v136
	v_pk_mul_f32 v[142:143], v[142:143], v[140:141] op_sel_hi:[1,0]
	v_pk_mul_f32 v[144:145], v[144:145], v[140:141] op_sel_hi:[1,0]
	v_pk_fma_f32 v[150:151], v[48:49], v[142:143], v[56:57]
	v_pk_fma_f32 v[152:153], v[50:51], v[144:145], v[58:59]
	global_store_dwordx4 v[130:131], v[150:153], off offset:16
	s_waitcnt vmcnt(14)
	v_lshlrev_b32_e32 v142, 16, v126
	v_and_b32_e32 v143, 0xffff0000, v126
	v_lshlrev_b32_e32 v144, 16, v127
	v_and_b32_e32 v145, 0xffff0000, v127
	v_sub_f32_e32 v142, v142, v136
	v_sub_f32_e32 v143, v143, v136
	v_sub_f32_e32 v144, v144, v136
	v_sub_f32_e32 v145, v145, v136
	v_pk_mul_f32 v[142:143], v[142:143], v[140:141] op_sel_hi:[1,0]
	v_pk_mul_f32 v[144:145], v[144:145], v[140:141] op_sel_hi:[1,0]
	v_pk_fma_f32 v[154:155], v[60:61], v[142:143], v[68:69]
	v_pk_fma_f32 v[156:157], v[62:63], v[144:145], v[70:71]
	global_store_dwordx4 v[130:131], v[154:157], off offset:2048
	v_lshlrev_b32_e32 v142, 16, v128
	v_and_b32_e32 v143, 0xffff0000, v128
	v_lshlrev_b32_e32 v144, 16, v129
	v_and_b32_e32 v145, 0xffff0000, v129
	v_sub_f32_e32 v142, v142, v136
	v_sub_f32_e32 v143, v143, v136
	v_sub_f32_e32 v144, v144, v136
	v_sub_f32_e32 v145, v145, v136
	v_pk_mul_f32 v[142:143], v[142:143], v[140:141] op_sel_hi:[1,0]
	v_pk_mul_f32 v[144:145], v[144:145], v[140:141] op_sel_hi:[1,0]
	v_pk_fma_f32 v[158:159], v[64:65], v[142:143], v[72:73]
	v_pk_fma_f32 v[160:161], v[66:67], v[144:145], v[74:75]
	global_store_dwordx4 v[130:131], v[158:161], off offset:2064
	s_branch .Lfln2_main
